# v12 + one extra wait-state pad between v_readlane of the rope table base and its first use as a load base
# speedup vs baseline: 1.0021x; 1.0021x over previous
; __device__ __forceinline__ void epi_store(const f32x4 (&acc)[2][2][4][2], const Unit& u, int wr, int wc, int fr, int fq, const EpiP& e) {
;     ...
;                 if (kind != 0 && row < MLAT) {
;                     const int t = row & (SEQ - 1); const int pos = (kind == 1) ? (t >> 6) : (t & 63);
;                     const f32x4 t0 = *(const f32x4*)(e.rope + (pos * 16 + 4 * fq) * 2), t1 = *(const f32x4*)(e.rope + (pos * 16 + 4 * fq) * 2 + 4);
;                     const float cs[4] = {t0[0], t0[2], t1[0], t1[2]}, sn[4] = {t0[1], t0[3], t1[1], t1[3]};
.Lrp_kdone:
	s_cmp_lt_u32 s87, 0x80
	s_cselect_b32 s20, s20, 0
	s_cselect_b32 s21, s21, 0
	s_or_b32 s27, s20, s21
	s_cmp_eq_u32 s27, 0
	s_cbranch_scc1 .Lrp_loaded
	v_readlane_b32 s22, v253, 6
	v_readlane_b32 s23, v253, 7
	s_nop 1
	s_cmp_eq_u32 s27, 1
	s_cbranch_scc0 .Lrp_ld2
	s_lshl_b32 s18, s87, 2
	s_add_i32 s18, s18, s16
	s_and_b32 s26, s18, 31
	s_lshl_b32 s26, s26, 7
	s_add_u32 s24, s22, s26
	s_addc_u32 s25, s23, 0
	s_add_i32 s18, s18, 2
	s_and_b32 s26, s18, 31
	s_lshl_b32 s26, s26, 7
	s_add_u32 s22, s22, s26
	s_addc_u32 s23, s23, 0
	global_load_dwordx4 v[160:163], v221, s[24:25]
	global_load_dwordx4 v[164:167], v221, s[24:25] offset:16
	global_load_dwordx4 v[168:171], v221, s[22:23]
	global_load_dwordx4 v[172:175], v221, s[22:23] offset:16
	s_branch .Lrp_ldw
